# rows phases: the four bf16 y-chunk loads of a row issued together instead of load-wait pairs (on top of the hand-scheduled RWKV scan)
# speedup vs baseline: 1.0318x; 1.0008x over previous
.LBB0_1219:
	s_or_b64 exec, exec, s[24:25]
	v_cmp_gt_i32_e64 s[4:5], s67, v98
	s_xor_b64 s[24:25], s[16:17], -1
	v_lshlrev_b64 v[126:127], 11, v[98:99]
	s_or_b64 s[4:5], s[24:25], s[4:5]
	v_lshl_add_u64 v[140:141], v[102:103], 0, v[126:127]
	s_and_saveexec_b64 s[24:25], s[4:5]
	s_xor_b64 s[24:25], exec, s[24:25]
	s_cbranch_execz .LBB0_1221
	global_load_dwordx2 v[134:135], v[140:141], off nt
	global_load_dwordx2 v[138:139], v[140:141], off offset:512 nt
	global_load_dwordx2 v[146:147], v[140:141], off offset:1024 nt
	global_load_dwordx2 v[140:141], v[140:141], off offset:1536 nt
	s_waitcnt vmcnt(3)
	v_lshlrev_b32_e32 v128, 16, v134
	v_and_b32_e32 v129, 0xffff0000, v134
	v_lshlrev_b32_e32 v134, 16, v135
	v_and_b32_e32 v135, 0xffff0000, v135

.LBB0_1224:
	s_or_b64 exec, exec, s[24:25]
	s_and_saveexec_b64 s[24:25], s[4:5]
	s_xor_b64 s[24:25], exec, s[24:25]
	s_cbranch_execz .LBB0_1226
	s_waitcnt vmcnt(0)
	v_lshlrev_b32_e32 v136, 16, v138
	v_and_b32_e32 v137, 0xffff0000, v138
	v_lshlrev_b32_e32 v138, 16, v139
	v_and_b32_e32 v139, 0xffff0000, v139

.LBB0_1229:
	s_or_b64 exec, exec, s[24:25]
	s_and_saveexec_b64 s[24:25], s[4:5]
	s_xor_b64 s[24:25], exec, s[24:25]
	s_cbranch_execz .LBB0_1231
	s_waitcnt vmcnt(0)
	v_lshlrev_b32_e32 v144, 16, v146
	v_and_b32_e32 v145, 0xffff0000, v146
	v_lshlrev_b32_e32 v146, 16, v147
	v_and_b32_e32 v147, 0xffff0000, v147

.LBB0_1234:
	s_or_b64 exec, exec, s[24:25]
	s_and_saveexec_b64 s[24:25], s[4:5]
	s_xor_b64 s[4:5], exec, s[24:25]
	s_cbranch_execz .LBB0_1236
	s_waitcnt vmcnt(0)
	v_and_b32_e32 v151, 0xffff0000, v140
	v_lshlrev_b32_e32 v150, 16, v140
	v_and_b32_e32 v149, 0xffff0000, v141
	v_lshlrev_b32_e32 v148, 16, v141

.LBB0_1545:
	s_or_b64 exec, exec, s[20:21]
	v_cmp_gt_i32_e32 vcc, s67, v100
	s_xor_b64 s[20:21], s[16:17], -1
	v_lshlrev_b64 v[118:119], 11, v[100:101]
	s_or_b64 s[20:21], s[20:21], vcc
	v_lshl_add_u64 v[128:129], v[102:103], 0, v[118:119]
	s_and_saveexec_b64 s[22:23], s[20:21]
	s_xor_b64 s[22:23], exec, s[22:23]
	s_cbranch_execz .LBB0_1547
	global_load_dwordx2 v[120:121], v[128:129], off nt
	global_load_dwordx2 v[136:137], v[128:129], off offset:512 nt
	global_load_dwordx2 v[140:141], v[128:129], off offset:1024 nt
	global_load_dwordx2 v[144:145], v[128:129], off offset:1536 nt
	s_waitcnt vmcnt(3)
	v_lshlrev_b32_e32 v124, 16, v120
	v_and_b32_e32 v125, 0xffff0000, v120
	v_lshlrev_b32_e32 v126, 16, v121
	v_and_b32_e32 v127, 0xffff0000, v121

.LBB0_1549:
	s_or_b64 exec, exec, s[22:23]
	s_and_saveexec_b64 s[22:23], s[20:21]
	s_xor_b64 s[22:23], exec, s[22:23]
	s_cbranch_execz .LBB0_1551
	s_waitcnt vmcnt(0)
	v_lshlrev_b32_e32 v134, 16, v136
	v_and_b32_e32 v135, 0xffff0000, v136
	v_lshlrev_b32_e32 v136, 16, v137
	v_and_b32_e32 v137, 0xffff0000, v137
	s_andn2_saveexec_b64 s[22:23], s[22:23]
	s_cbranch_execz .LBB0_1553
	s_branch .LBB0_1552

.LBB0_1553:
	s_or_b64 exec, exec, s[22:23]
	s_and_saveexec_b64 s[22:23], s[20:21]
	s_xor_b64 s[22:23], exec, s[22:23]
	s_cbranch_execz .LBB0_1555
	s_waitcnt vmcnt(0)
	v_lshlrev_b32_e32 v138, 16, v140
	v_and_b32_e32 v139, 0xffff0000, v140
	v_lshlrev_b32_e32 v140, 16, v141
	v_and_b32_e32 v141, 0xffff0000, v141
	s_andn2_saveexec_b64 s[22:23], s[22:23]
	s_cbranch_execz .LBB0_1557
	s_branch .LBB0_1556

.LBB0_1557:
	s_or_b64 exec, exec, s[22:23]
	s_and_saveexec_b64 s[22:23], s[20:21]
	s_xor_b64 s[20:21], exec, s[22:23]
	s_cbranch_execz .LBB0_1559
	s_waitcnt vmcnt(0)
	v_lshlrev_b32_e32 v142, 16, v144
	v_and_b32_e32 v143, 0xffff0000, v144
	v_lshlrev_b32_e32 v144, 16, v145
	v_and_b32_e32 v145, 0xffff0000, v145
	s_andn2_saveexec_b64 s[20:21], s[20:21]
	s_cbranch_execnz .LBB0_1560
	s_branch .LBB0_1561
